# DMA issue pacing: one LDS-DMA piece per MFMA pair for the six non-early pieces (was two per pair over three groups)
# speedup vs baseline: 1.0108x; 1.0108x over previous
; template <int EPI, int MI>
; DI void gemm_tile(const GemmDesc& g, int tm, int tn, char* smem) {
;     ...
;   G_GLDS(0, 0);
;   asm volatile("s_waitcnt vmcnt(0)" ::: "memory");
;   __syncthreads();
;   for (int kt = 0; kt < nk; kt += 2) {
;     if (kt + 1 < nk) G_GLDS(kt + 1, 1);
;     G_COMPUTE(0);
;     asm volatile("s_waitcnt vmcnt(0)" ::: "memory");
;     __syncthreads();
;     if (kt + 1 < nk) {
;       if (kt + 2 < nk) G_GLDS(kt + 2, 0);
;       G_COMPUTE(1);
;       asm volatile("s_waitcnt vmcnt(0)" ::: "memory");
;       __syncthreads();
;     }
.Lga_loop:
	ds_read_b128 v[232:235], v162 offset:8192
	s_waitcnt lgkmcnt(2)
	v_mfma_f32_32x32x16_bf16 v[80:95], v[224:227], v[236:239], v[80:95]
	v_mfma_f32_32x32x16_bf16 v[64:79], v[224:227], v[240:243], v[64:79]
	s_add_u32 m0, s100, 0xa000
	v_lshl_add_u64 v[106:107], v[174:175], 0, s[28:29]
	global_load_lds_dwordx4 v[106:107], off
	ds_read_b128 v[244:247], v167 offset:49152
	ds_read_b128 v[248:251], v167 offset:53248
	ds_read_b128 v[224:227], v163
	s_waitcnt lgkmcnt(4)
	v_mfma_f32_32x32x16_bf16 v[48:63], v[228:231], v[236:239], v[48:63]
	v_mfma_f32_32x32x16_bf16 v[32:47], v[228:231], v[240:243], v[32:47]
	s_add_u32 m0, s100, 0xb000
	v_lshl_add_u64 v[106:107], v[174:175], 0, s[30:31]
	global_load_lds_dwordx4 v[106:107], off
	v_lshl_add_u64 v[174:175], v[174:175], 0, s[18:19]
	ds_read_b128 v[228:231], v163 offset:4096
	s_waitcnt lgkmcnt(4)
	v_mfma_f32_32x32x16_bf16 v[16:31], v[232:235], v[236:239], v[16:31]
	v_mfma_f32_32x32x16_bf16 v[0:15], v[232:235], v[240:243], v[0:15]
	s_add_u32 m0, s100, 0x10000
	v_lshl_add_u64 v[106:107], v[176:177], 0, s[18:19]
	global_load_lds_dwordx4 v[106:107], off
	ds_read_b128 v[232:235], v163 offset:8192
	s_waitcnt lgkmcnt(2)
	v_mfma_f32_32x32x16_bf16 v[80:95], v[224:227], v[244:247], v[80:95]
	v_mfma_f32_32x32x16_bf16 v[64:79], v[224:227], v[248:251], v[64:79]
	s_add_u32 m0, s100, 0x11000
	v_lshl_add_u64 v[106:107], v[176:177], 0, s[42:43]
	global_load_lds_dwordx4 v[106:107], off
	ds_read_b128 v[236:239], v168 offset:49152
	ds_read_b128 v[240:243], v168 offset:53248
	ds_read_b128 v[224:227], v164
	s_waitcnt lgkmcnt(4)
	v_mfma_f32_32x32x16_bf16 v[48:63], v[228:231], v[244:247], v[48:63]
	v_mfma_f32_32x32x16_bf16 v[32:47], v[228:231], v[248:251], v[32:47]
	s_mov_b64 s[16:17], 0x20080
	s_add_u32 m0, s100, 0x12000
	v_lshl_add_u64 v[106:107], v[176:177], 0, s[16:17]
	global_load_lds_dwordx4 v[106:107], off
	ds_read_b128 v[228:231], v164 offset:4096
	s_waitcnt lgkmcnt(4)
	v_mfma_f32_32x32x16_bf16 v[16:31], v[232:235], v[244:247], v[16:31]
	v_mfma_f32_32x32x16_bf16 v[0:15], v[232:235], v[248:251], v[0:15]
	s_mov_b64 s[16:17], 0x30080
	s_add_u32 m0, s100, 0x13000
	v_lshl_add_u64 v[106:107], v[176:177], 0, s[16:17]
	global_load_lds_dwordx4 v[106:107], off
	v_lshl_add_u64 v[176:177], v[176:177], 0, s[18:19]
	ds_read_b128 v[232:235], v164 offset:8192
	s_waitcnt lgkmcnt(2)
	v_mfma_f32_32x32x16_bf16 v[80:95], v[224:227], v[236:239], v[80:95]
	v_mfma_f32_32x32x16_bf16 v[64:79], v[224:227], v[240:243], v[64:79]
	ds_read_b128 v[244:247], v169 offset:49152
	ds_read_b128 v[248:251], v169 offset:53248
	ds_read_b128 v[224:227], v165
	s_waitcnt lgkmcnt(4)
	v_mfma_f32_32x32x16_bf16 v[48:63], v[228:231], v[236:239], v[48:63]
	v_mfma_f32_32x32x16_bf16 v[32:47], v[228:231], v[240:243], v[32:47]
	ds_read_b128 v[228:231], v165 offset:4096
	s_waitcnt lgkmcnt(4)
	v_mfma_f32_32x32x16_bf16 v[16:31], v[232:235], v[236:239], v[16:31]
	v_mfma_f32_32x32x16_bf16 v[0:15], v[232:235], v[240:243], v[0:15]
	ds_read_b128 v[232:235], v165 offset:8192
	s_waitcnt lgkmcnt(2)
	v_mfma_f32_32x32x16_bf16 v[80:95], v[224:227], v[244:247], v[80:95]
	v_mfma_f32_32x32x16_bf16 v[64:79], v[224:227], v[248:251], v[64:79]
	s_waitcnt lgkmcnt(0)
	s_waitcnt vmcnt(0)
	s_barrier
	s_cmp_eq_u32 s15, 14
	s_cbranch_scc1 .Lga_noearly
	s_mov_b32 m0, s100
	v_lshl_add_u64 v[106:107], v[174:175], 0, s[96:97]
	global_load_lds_dwordx4 v[106:107], off
	s_add_u32 m0, s100, 0x1000
	v_lshl_add_u64 v[106:107], v[174:175], 0, s[50:51]
	global_load_lds_dwordx4 v[106:107], off
	s_add_u32 m0, s100, 0x2000
	v_lshl_add_u64 v[106:107], v[174:175], 0, s[24:25]
	global_load_lds_dwordx4 v[106:107], off
	s_add_u32 m0, s100, 0x3000
	v_lshl_add_u64 v[106:107], v[174:175], 0, s[26:27]
	global_load_lds_dwordx4 v[106:107], off
; template <int EPI, int MI>
; DI void gemm_tile(const GemmDesc& g, int tm, int tn, char* smem) {
;     ...
;   for (int kt = 0; kt < nk; kt += 2) {
;     if (kt + 1 < nk) G_GLDS(kt + 1, 1);
;     G_COMPUTE(0);
;     asm volatile("s_waitcnt vmcnt(0)" ::: "memory");
;     __syncthreads();
;     if (kt + 1 < nk) {
;       if (kt + 2 < nk) G_GLDS(kt + 2, 0);
;       G_COMPUTE(1);
;       asm volatile("s_waitcnt vmcnt(0)" ::: "memory");
;       __syncthreads();
;     }
.Lga_noearly:
	ds_read_b128 v[236:239], v170
	ds_read_b128 v[240:243], v170 offset:4096
	ds_read_b128 v[224:227], v162 offset:24576
	v_mfma_f32_32x32x16_bf16 v[48:63], v[228:231], v[244:247], v[48:63]
	v_mfma_f32_32x32x16_bf16 v[32:47], v[228:231], v[248:251], v[32:47]
	ds_read_b128 v[228:231], v162 offset:28672
	v_mfma_f32_32x32x16_bf16 v[16:31], v[232:235], v[244:247], v[16:31]
	v_mfma_f32_32x32x16_bf16 v[0:15], v[232:235], v[248:251], v[0:15]
	s_cmp_eq_u32 s15, 14
	s_cbranch_scc1 .Lga_last
	ds_read_b128 v[232:235], v162 offset:32768
	s_waitcnt lgkmcnt(2)
	v_mfma_f32_32x32x16_bf16 v[80:95], v[224:227], v[236:239], v[80:95]
	v_mfma_f32_32x32x16_bf16 v[64:79], v[224:227], v[240:243], v[64:79]
	s_add_u32 m0, s100, 0x4000
	v_lshl_add_u64 v[106:107], v[174:175], 0, s[28:29]
	global_load_lds_dwordx4 v[106:107], off
	ds_read_b128 v[244:247], v171
	ds_read_b128 v[248:251], v171 offset:4096
	ds_read_b128 v[224:227], v163 offset:24576
	s_waitcnt lgkmcnt(4)
	v_mfma_f32_32x32x16_bf16 v[48:63], v[228:231], v[236:239], v[48:63]
	v_mfma_f32_32x32x16_bf16 v[32:47], v[228:231], v[240:243], v[32:47]
	s_add_u32 m0, s100, 0x5000
	v_lshl_add_u64 v[106:107], v[174:175], 0, s[30:31]
	global_load_lds_dwordx4 v[106:107], off
	v_lshl_add_u64 v[174:175], v[174:175], 0, s[18:19]
	ds_read_b128 v[228:231], v163 offset:28672
	s_waitcnt lgkmcnt(4)
	v_mfma_f32_32x32x16_bf16 v[16:31], v[232:235], v[236:239], v[16:31]
	v_mfma_f32_32x32x16_bf16 v[0:15], v[232:235], v[240:243], v[0:15]
	s_add_u32 m0, s100, 0xc000
	v_lshl_add_u64 v[106:107], v[176:177], 0, s[18:19]
	global_load_lds_dwordx4 v[106:107], off
	ds_read_b128 v[232:235], v163 offset:32768
	s_waitcnt lgkmcnt(2)
	v_mfma_f32_32x32x16_bf16 v[80:95], v[224:227], v[244:247], v[80:95]
	v_mfma_f32_32x32x16_bf16 v[64:79], v[224:227], v[248:251], v[64:79]
	s_add_u32 m0, s100, 0xd000
	v_lshl_add_u64 v[106:107], v[176:177], 0, s[42:43]
	global_load_lds_dwordx4 v[106:107], off
	ds_read_b128 v[236:239], v172
	ds_read_b128 v[240:243], v172 offset:4096
	ds_read_b128 v[224:227], v164 offset:24576
	s_waitcnt lgkmcnt(4)
	v_mfma_f32_32x32x16_bf16 v[48:63], v[228:231], v[244:247], v[48:63]
	v_mfma_f32_32x32x16_bf16 v[32:47], v[228:231], v[248:251], v[32:47]
	s_mov_b64 s[16:17], 0x20080
	s_add_u32 m0, s100, 0xe000
	v_lshl_add_u64 v[106:107], v[176:177], 0, s[16:17]
	global_load_lds_dwordx4 v[106:107], off
	ds_read_b128 v[228:231], v164 offset:28672
	s_waitcnt lgkmcnt(4)
	v_mfma_f32_32x32x16_bf16 v[16:31], v[232:235], v[244:247], v[16:31]
	v_mfma_f32_32x32x16_bf16 v[0:15], v[232:235], v[248:251], v[0:15]
	s_mov_b64 s[16:17], 0x30080
	s_add_u32 m0, s100, 0xf000
	v_lshl_add_u64 v[106:107], v[176:177], 0, s[16:17]
	global_load_lds_dwordx4 v[106:107], off
	v_lshl_add_u64 v[176:177], v[176:177], 0, s[18:19]
	ds_read_b128 v[232:235], v164 offset:32768
	s_waitcnt lgkmcnt(2)
	v_mfma_f32_32x32x16_bf16 v[80:95], v[224:227], v[236:239], v[80:95]
	v_mfma_f32_32x32x16_bf16 v[64:79], v[224:227], v[240:243], v[64:79]
	ds_read_b128 v[244:247], v173
	ds_read_b128 v[248:251], v173 offset:4096
	ds_read_b128 v[224:227], v165 offset:24576
	s_waitcnt lgkmcnt(4)
	v_mfma_f32_32x32x16_bf16 v[48:63], v[228:231], v[236:239], v[48:63]
	v_mfma_f32_32x32x16_bf16 v[32:47], v[228:231], v[240:243], v[32:47]
	ds_read_b128 v[228:231], v165 offset:28672
	s_waitcnt lgkmcnt(4)
	v_mfma_f32_32x32x16_bf16 v[16:31], v[232:235], v[236:239], v[16:31]
	v_mfma_f32_32x32x16_bf16 v[0:15], v[232:235], v[240:243], v[0:15]
	ds_read_b128 v[232:235], v165 offset:32768
	s_waitcnt lgkmcnt(2)
	v_mfma_f32_32x32x16_bf16 v[80:95], v[224:227], v[244:247], v[80:95]
	v_mfma_f32_32x32x16_bf16 v[64:79], v[224:227], v[248:251], v[64:79]
	s_waitcnt lgkmcnt(0)
	s_waitcnt vmcnt(0)
	s_barrier
	s_add_u32 m0, s100, 0x6000
	v_lshl_add_u64 v[106:107], v[174:175], 0, s[96:97]
	global_load_lds_dwordx4 v[106:107], off
	s_add_u32 m0, s100, 0x7000
	v_lshl_add_u64 v[106:107], v[174:175], 0, s[50:51]
	global_load_lds_dwordx4 v[106:107], off
	s_add_u32 m0, s100, 0x8000
	v_lshl_add_u64 v[106:107], v[174:175], 0, s[24:25]
	global_load_lds_dwordx4 v[106:107], off
	s_add_u32 m0, s100, 0x9000
	v_lshl_add_u64 v[106:107], v[174:175], 0, s[26:27]
	global_load_lds_dwordx4 v[106:107], off
	ds_read_b128 v[236:239], v166 offset:49152
	ds_read_b128 v[240:243], v166 offset:53248
	ds_read_b128 v[224:227], v162
	v_mfma_f32_32x32x16_bf16 v[48:63], v[228:231], v[244:247], v[48:63]
	v_mfma_f32_32x32x16_bf16 v[32:47], v[228:231], v[248:251], v[32:47]
	ds_read_b128 v[228:231], v162 offset:4096
	v_mfma_f32_32x32x16_bf16 v[16:31], v[232:235], v[244:247], v[16:31]
	v_mfma_f32_32x32x16_bf16 v[0:15], v[232:235], v[248:251], v[0:15]
	s_add_u32 s15, s15, 2
	s_branch .Lga_loop

; template <int EPI, int MI>
; DI void gemm_tile(const GemmDesc& g, int tm, int tn, char* smem) {
;     ...
;   G_GLDS(0, 0);
;   asm volatile("s_waitcnt vmcnt(0)" ::: "memory");
;   __syncthreads();
;   for (int kt = 0; kt < nk; kt += 2) {
;     if (kt + 1 < nk) G_GLDS(kt + 1, 1);
;     G_COMPUTE(0);
;     asm volatile("s_waitcnt vmcnt(0)" ::: "memory");
;     __syncthreads();
;     if (kt + 1 < nk) {
;       if (kt + 2 < nk) G_GLDS(kt + 2, 0);
;       G_COMPUTE(1);
;       asm volatile("s_waitcnt vmcnt(0)" ::: "memory");
;       __syncthreads();
;     }
.Lgw_loop:
	ds_read_b128 v[232:235], v162 offset:8192
	s_waitcnt lgkmcnt(2)
	v_mfma_f32_32x32x16_bf16 v[80:95], v[224:227], v[236:239], v[80:95]
	v_mfma_f32_32x32x16_bf16 v[64:79], v[224:227], v[240:243], v[64:79]
	s_add_u32 m0, s100, 0xa000
	v_lshl_add_u64 v[106:107], v[252:253], 0, s[28:29]
	global_load_lds_dwordx4 v[106:107], off
	ds_read_b128 v[244:247], v167 offset:49152
	ds_read_b128 v[248:251], v167 offset:53248
	ds_read_b128 v[224:227], v163
	s_waitcnt lgkmcnt(4)
	v_mfma_f32_32x32x16_bf16 v[48:63], v[228:231], v[236:239], v[48:63]
	v_mfma_f32_32x32x16_bf16 v[32:47], v[228:231], v[240:243], v[32:47]
	s_add_u32 m0, s100, 0xb000
	v_lshl_add_u64 v[106:107], v[252:253], 0, s[30:31]
	global_load_lds_dwordx4 v[106:107], off
	v_lshl_add_u64 v[252:253], v[252:253], 0, s[0:1]
	ds_read_b128 v[228:231], v163 offset:4096
	s_waitcnt lgkmcnt(4)
	v_mfma_f32_32x32x16_bf16 v[16:31], v[232:235], v[236:239], v[16:31]
	v_mfma_f32_32x32x16_bf16 v[0:15], v[232:235], v[240:243], v[0:15]
	s_mov_b64 s[16:17], 0x2100080
	s_add_u32 m0, s100, 0x10000
	v_lshl_add_u64 v[106:107], v[254:255], 0, s[16:17]
	global_load_lds_dwordx4 v[106:107], off
	ds_read_b128 v[232:235], v163 offset:8192
	s_waitcnt lgkmcnt(2)
	v_mfma_f32_32x32x16_bf16 v[80:95], v[224:227], v[244:247], v[80:95]
	v_mfma_f32_32x32x16_bf16 v[64:79], v[224:227], v[248:251], v[64:79]
	s_mov_b64 s[16:17], 0x2110080
	s_add_u32 m0, s100, 0x11000
	v_lshl_add_u64 v[106:107], v[254:255], 0, s[16:17]
	global_load_lds_dwordx4 v[106:107], off
	ds_read_b128 v[236:239], v168 offset:49152
	ds_read_b128 v[240:243], v168 offset:53248
	ds_read_b128 v[224:227], v164
	s_waitcnt lgkmcnt(4)
	v_mfma_f32_32x32x16_bf16 v[48:63], v[228:231], v[244:247], v[48:63]
	v_mfma_f32_32x32x16_bf16 v[32:47], v[228:231], v[248:251], v[32:47]
	s_mov_b64 s[16:17], 0x2120080
	s_add_u32 m0, s100, 0x12000
	v_lshl_add_u64 v[106:107], v[254:255], 0, s[16:17]
	global_load_lds_dwordx4 v[106:107], off
	ds_read_b128 v[228:231], v164 offset:4096
	s_waitcnt lgkmcnt(4)
	v_mfma_f32_32x32x16_bf16 v[16:31], v[232:235], v[244:247], v[16:31]
	v_mfma_f32_32x32x16_bf16 v[0:15], v[232:235], v[248:251], v[0:15]
	s_mov_b64 s[16:17], 0x2130080
	s_add_u32 m0, s100, 0x13000
	v_lshl_add_u64 v[106:107], v[254:255], 0, s[16:17]
	global_load_lds_dwordx4 v[106:107], off
	v_lshl_add_u64 v[254:255], v[254:255], 0, s[0:1]
	ds_read_b128 v[232:235], v164 offset:8192
	s_waitcnt lgkmcnt(2)
	v_mfma_f32_32x32x16_bf16 v[80:95], v[224:227], v[236:239], v[80:95]
	v_mfma_f32_32x32x16_bf16 v[64:79], v[224:227], v[240:243], v[64:79]
	ds_read_b128 v[244:247], v169 offset:49152
	ds_read_b128 v[248:251], v169 offset:53248
	ds_read_b128 v[224:227], v165
	s_waitcnt lgkmcnt(4)
	v_mfma_f32_32x32x16_bf16 v[48:63], v[228:231], v[236:239], v[48:63]
	v_mfma_f32_32x32x16_bf16 v[32:47], v[228:231], v[240:243], v[32:47]
	ds_read_b128 v[228:231], v165 offset:4096
	s_waitcnt lgkmcnt(4)
	v_mfma_f32_32x32x16_bf16 v[16:31], v[232:235], v[236:239], v[16:31]
	v_mfma_f32_32x32x16_bf16 v[0:15], v[232:235], v[240:243], v[0:15]
	ds_read_b128 v[232:235], v165 offset:8192
	s_waitcnt lgkmcnt(2)
	v_mfma_f32_32x32x16_bf16 v[80:95], v[224:227], v[244:247], v[80:95]
	v_mfma_f32_32x32x16_bf16 v[64:79], v[224:227], v[248:251], v[64:79]
	s_waitcnt lgkmcnt(0)
	s_waitcnt vmcnt(0)
	s_barrier
	s_cmp_eq_u32 s101, 14
	s_cbranch_scc1 .Lgw_noearly
	s_mov_b32 m0, s100
	v_lshl_add_u64 v[106:107], v[252:253], 0, s[96:97]
	global_load_lds_dwordx4 v[106:107], off
	s_add_u32 m0, s100, 0x1000
	v_lshl_add_u64 v[106:107], v[252:253], 0, s[50:51]
	global_load_lds_dwordx4 v[106:107], off
	s_add_u32 m0, s100, 0x2000
	v_lshl_add_u64 v[106:107], v[252:253], 0, s[24:25]
	global_load_lds_dwordx4 v[106:107], off
	s_add_u32 m0, s100, 0x3000
	v_lshl_add_u64 v[106:107], v[252:253], 0, s[26:27]
	global_load_lds_dwordx4 v[106:107], off
; template <int EPI, int MI>
; DI void gemm_tile(const GemmDesc& g, int tm, int tn, char* smem) {
;     ...
;   for (int kt = 0; kt < nk; kt += 2) {
;     if (kt + 1 < nk) G_GLDS(kt + 1, 1);
;     G_COMPUTE(0);
;     asm volatile("s_waitcnt vmcnt(0)" ::: "memory");
;     __syncthreads();
;     if (kt + 1 < nk) {
;       if (kt + 2 < nk) G_GLDS(kt + 2, 0);
;       G_COMPUTE(1);
;       asm volatile("s_waitcnt vmcnt(0)" ::: "memory");
;       __syncthreads();
;     }
.Lgw_noearly:
	ds_read_b128 v[236:239], v170
	ds_read_b128 v[240:243], v170 offset:4096
	ds_read_b128 v[224:227], v162 offset:24576
	v_mfma_f32_32x32x16_bf16 v[48:63], v[228:231], v[244:247], v[48:63]
	v_mfma_f32_32x32x16_bf16 v[32:47], v[228:231], v[248:251], v[32:47]
	ds_read_b128 v[228:231], v162 offset:28672
	v_mfma_f32_32x32x16_bf16 v[16:31], v[232:235], v[244:247], v[16:31]
	v_mfma_f32_32x32x16_bf16 v[0:15], v[232:235], v[248:251], v[0:15]
	s_cmp_eq_u32 s101, 14
	s_cbranch_scc1 .Lgw_last
	ds_read_b128 v[232:235], v162 offset:32768
	s_waitcnt lgkmcnt(2)
	v_mfma_f32_32x32x16_bf16 v[80:95], v[224:227], v[236:239], v[80:95]
	v_mfma_f32_32x32x16_bf16 v[64:79], v[224:227], v[240:243], v[64:79]
	s_add_u32 m0, s100, 0x4000
	v_lshl_add_u64 v[106:107], v[252:253], 0, s[28:29]
	global_load_lds_dwordx4 v[106:107], off
	ds_read_b128 v[244:247], v171
	ds_read_b128 v[248:251], v171 offset:4096
	ds_read_b128 v[224:227], v163 offset:24576
	s_waitcnt lgkmcnt(4)
	v_mfma_f32_32x32x16_bf16 v[48:63], v[228:231], v[236:239], v[48:63]
	v_mfma_f32_32x32x16_bf16 v[32:47], v[228:231], v[240:243], v[32:47]
	s_add_u32 m0, s100, 0x5000
	v_lshl_add_u64 v[106:107], v[252:253], 0, s[30:31]
	global_load_lds_dwordx4 v[106:107], off
	v_lshl_add_u64 v[252:253], v[252:253], 0, s[0:1]
	ds_read_b128 v[228:231], v163 offset:28672
	s_waitcnt lgkmcnt(4)
	v_mfma_f32_32x32x16_bf16 v[16:31], v[232:235], v[236:239], v[16:31]
	v_mfma_f32_32x32x16_bf16 v[0:15], v[232:235], v[240:243], v[0:15]
	s_mov_b64 s[16:17], 0x2100080
	s_add_u32 m0, s100, 0xc000
	v_lshl_add_u64 v[106:107], v[254:255], 0, s[16:17]
	global_load_lds_dwordx4 v[106:107], off
	ds_read_b128 v[232:235], v163 offset:32768
	s_waitcnt lgkmcnt(2)
	v_mfma_f32_32x32x16_bf16 v[80:95], v[224:227], v[244:247], v[80:95]
	v_mfma_f32_32x32x16_bf16 v[64:79], v[224:227], v[248:251], v[64:79]
	s_mov_b64 s[16:17], 0x2110080
	s_add_u32 m0, s100, 0xd000
	v_lshl_add_u64 v[106:107], v[254:255], 0, s[16:17]
	global_load_lds_dwordx4 v[106:107], off
	ds_read_b128 v[236:239], v172
	ds_read_b128 v[240:243], v172 offset:4096
	ds_read_b128 v[224:227], v164 offset:24576
	s_waitcnt lgkmcnt(4)
	v_mfma_f32_32x32x16_bf16 v[48:63], v[228:231], v[244:247], v[48:63]
	v_mfma_f32_32x32x16_bf16 v[32:47], v[228:231], v[248:251], v[32:47]
	s_mov_b64 s[16:17], 0x2120080
	s_add_u32 m0, s100, 0xe000
	v_lshl_add_u64 v[106:107], v[254:255], 0, s[16:17]
	global_load_lds_dwordx4 v[106:107], off
	ds_read_b128 v[228:231], v164 offset:28672
	s_waitcnt lgkmcnt(4)
	v_mfma_f32_32x32x16_bf16 v[16:31], v[232:235], v[244:247], v[16:31]
	v_mfma_f32_32x32x16_bf16 v[0:15], v[232:235], v[248:251], v[0:15]
	s_mov_b64 s[16:17], 0x2130080
	s_add_u32 m0, s100, 0xf000
	v_lshl_add_u64 v[106:107], v[254:255], 0, s[16:17]
	global_load_lds_dwordx4 v[106:107], off
	v_lshl_add_u64 v[254:255], v[254:255], 0, s[0:1]
	ds_read_b128 v[232:235], v164 offset:32768
	s_waitcnt lgkmcnt(2)
	v_mfma_f32_32x32x16_bf16 v[80:95], v[224:227], v[236:239], v[80:95]
	v_mfma_f32_32x32x16_bf16 v[64:79], v[224:227], v[240:243], v[64:79]
	ds_read_b128 v[244:247], v173
	ds_read_b128 v[248:251], v173 offset:4096
	ds_read_b128 v[224:227], v165 offset:24576
	s_waitcnt lgkmcnt(4)
	v_mfma_f32_32x32x16_bf16 v[48:63], v[228:231], v[236:239], v[48:63]
	v_mfma_f32_32x32x16_bf16 v[32:47], v[228:231], v[240:243], v[32:47]
	ds_read_b128 v[228:231], v165 offset:28672
	s_waitcnt lgkmcnt(4)
	v_mfma_f32_32x32x16_bf16 v[16:31], v[232:235], v[236:239], v[16:31]
	v_mfma_f32_32x32x16_bf16 v[0:15], v[232:235], v[240:243], v[0:15]
	ds_read_b128 v[232:235], v165 offset:32768
	s_waitcnt lgkmcnt(2)
	v_mfma_f32_32x32x16_bf16 v[80:95], v[224:227], v[244:247], v[80:95]
	v_mfma_f32_32x32x16_bf16 v[64:79], v[224:227], v[248:251], v[64:79]
	s_waitcnt lgkmcnt(0)
	s_waitcnt vmcnt(0)
	s_barrier
	s_add_u32 m0, s100, 0x6000
	v_lshl_add_u64 v[106:107], v[252:253], 0, s[96:97]
	global_load_lds_dwordx4 v[106:107], off
	s_add_u32 m0, s100, 0x7000
	v_lshl_add_u64 v[106:107], v[252:253], 0, s[50:51]
	global_load_lds_dwordx4 v[106:107], off
	s_add_u32 m0, s100, 0x8000
	v_lshl_add_u64 v[106:107], v[252:253], 0, s[24:25]
	global_load_lds_dwordx4 v[106:107], off
	s_add_u32 m0, s100, 0x9000
	v_lshl_add_u64 v[106:107], v[252:253], 0, s[26:27]
	global_load_lds_dwordx4 v[106:107], off
	ds_read_b128 v[236:239], v166 offset:49152
	ds_read_b128 v[240:243], v166 offset:53248
	ds_read_b128 v[224:227], v162
	v_mfma_f32_32x32x16_bf16 v[48:63], v[228:231], v[244:247], v[48:63]
	v_mfma_f32_32x32x16_bf16 v[32:47], v[228:231], v[248:251], v[32:47]
	ds_read_b128 v[228:231], v162 offset:4096
	v_mfma_f32_32x32x16_bf16 v[16:31], v[232:235], v[244:247], v[16:31]
	v_mfma_f32_32x32x16_bf16 v[0:15], v[232:235], v[248:251], v[0:15]
	s_add_u32 s101, s101, 2
	s_branch .Lgw_loop

; template <int EPI, int MI>
; DI void gemm_tile(const GemmDesc& g, int tm, int tn, char* smem) {
;     ...
;   const int rowA = wm * (32 * MI) + r, rowB = wn * 64 + r;
;   const int hk = hh ^ ((r & 7) ^ ((r >> 3) & 3));
;     ...
;   G_GLDS(0, 0);
;   asm volatile("s_waitcnt vmcnt(0)" ::: "memory");
;   __syncthreads();
;   for (int kt = 0; kt < nk; kt += 2) {
;     if (kt + 1 < nk) G_GLDS(kt + 1, 1);
;     G_COMPUTE(0);
;     asm volatile("s_waitcnt vmcnt(0)" ::: "memory");
;     __syncthreads();
;     if (kt + 1 < nk) {
;       if (kt + 2 < nk) G_GLDS(kt + 2, 0);
;       G_COMPUTE(1);
;       asm volatile("s_waitcnt vmcnt(0)" ::: "memory");
;       __syncthreads();
;     }
;   }
.Lgc_loop:
	ds_read_b128 v[248:251], v103 offset:32768
	ds_read_b128 v[252:255], v103 offset:36864
	ds_read_b128 v[232:235], v99
	s_waitcnt lgkmcnt(4)
	v_mfma_f32_32x32x16_bf16 v[48:63], v[224:227], v[240:243], v[48:63]
	v_mfma_f32_32x32x16_bf16 v[32:47], v[224:227], v[244:247], v[32:47]
	s_mov_b64 s[0:1], 0xb00080
	s_add_u32 m0, s100, 0xc000
	v_lshl_add_u64 v[106:107], v[74:75], 0, s[0:1]
	global_load_lds_dwordx4 v[106:107], off
	ds_read_b128 v[236:239], v99 offset:4096
	s_waitcnt lgkmcnt(4)
	v_mfma_f32_32x32x16_bf16 v[16:31], v[228:231], v[240:243], v[16:31]
	v_mfma_f32_32x32x16_bf16 v[0:15], v[228:231], v[244:247], v[0:15]
	s_mov_b64 s[0:1], 0xb10080
	s_add_u32 m0, s100, 0xd000
	v_lshl_add_u64 v[106:107], v[74:75], 0, s[0:1]
	global_load_lds_dwordx4 v[106:107], off
	ds_read_b128 v[240:243], v104 offset:32768
	ds_read_b128 v[244:247], v104 offset:36864
	ds_read_b128 v[224:227], v100
	s_waitcnt lgkmcnt(4)
	v_mfma_f32_32x32x16_bf16 v[48:63], v[232:235], v[248:251], v[48:63]
	v_mfma_f32_32x32x16_bf16 v[32:47], v[232:235], v[252:255], v[32:47]
	s_mov_b64 s[0:1], 0xb20080
	s_add_u32 m0, s100, 0xe000
	v_lshl_add_u64 v[106:107], v[74:75], 0, s[0:1]
	global_load_lds_dwordx4 v[106:107], off
	ds_read_b128 v[228:231], v100 offset:4096
	s_waitcnt lgkmcnt(4)
	v_mfma_f32_32x32x16_bf16 v[16:31], v[236:239], v[248:251], v[16:31]
	v_mfma_f32_32x32x16_bf16 v[0:15], v[236:239], v[252:255], v[0:15]
	s_mov_b64 s[0:1], 0xb30080
	s_add_u32 m0, s100, 0xf000
	v_lshl_add_u64 v[106:107], v[74:75], 0, s[0:1]
	global_load_lds_dwordx4 v[106:107], off
	v_lshl_add_u64 v[74:75], v[74:75], 0, s[44:45]
	ds_read_b128 v[248:251], v105 offset:32768
	ds_read_b128 v[252:255], v105 offset:36864
	ds_read_b128 v[232:235], v101
	s_waitcnt lgkmcnt(4)
	v_mfma_f32_32x32x16_bf16 v[48:63], v[224:227], v[240:243], v[48:63]
	v_mfma_f32_32x32x16_bf16 v[32:47], v[224:227], v[244:247], v[32:47]
	ds_read_b128 v[236:239], v101 offset:4096
	s_waitcnt lgkmcnt(4)
	v_mfma_f32_32x32x16_bf16 v[16:31], v[228:231], v[240:243], v[16:31]
	v_mfma_f32_32x32x16_bf16 v[0:15], v[228:231], v[244:247], v[0:15]
	s_waitcnt lgkmcnt(0)
	s_waitcnt vmcnt(0)
	s_barrier
	s_cmp_eq_u32 s101, 14
	s_cbranch_scc1 .Lgc_noearly
	s_mov_b32 m0, s100
	v_lshl_add_u64 v[106:107], v[72:73], 0, s[96:97]
	global_load_lds_dwordx4 v[106:107], off
	s_add_u32 m0, s100, 0x1000
	v_lshl_add_u64 v[106:107], v[72:73], 0, s[50:51]
	global_load_lds_dwordx4 v[106:107], off
	s_add_u32 m0, s100, 0x2000
	v_lshl_add_u64 v[106:107], v[72:73], 0, s[24:25]
	global_load_lds_dwordx4 v[106:107], off
	s_add_u32 m0, s100, 0x3000
	v_lshl_add_u64 v[106:107], v[72:73], 0, s[26:27]
	global_load_lds_dwordx4 v[106:107], off
	v_lshl_add_u64 v[72:73], v[72:73], 0, s[44:45]
.Lgc_noearly:
	ds_read_b128 v[240:243], v102 offset:49152
	ds_read_b128 v[244:247], v102 offset:53248
	ds_read_b128 v[224:227], v98 offset:16384
	v_mfma_f32_32x32x16_bf16 v[48:63], v[232:235], v[248:251], v[48:63]
	v_mfma_f32_32x32x16_bf16 v[32:47], v[232:235], v[252:255], v[32:47]
	ds_read_b128 v[228:231], v98 offset:20480
	v_mfma_f32_32x32x16_bf16 v[16:31], v[236:239], v[248:251], v[16:31]
	v_mfma_f32_32x32x16_bf16 v[0:15], v[236:239], v[252:255], v[0:15]
	s_cmp_eq_u32 s101, 14
	s_cbranch_scc1 .Lgc_last
	ds_read_b128 v[248:251], v103 offset:49152
	ds_read_b128 v[252:255], v103 offset:53248
	ds_read_b128 v[232:235], v99 offset:16384
	s_waitcnt lgkmcnt(4)
	v_mfma_f32_32x32x16_bf16 v[48:63], v[224:227], v[240:243], v[48:63]
	v_mfma_f32_32x32x16_bf16 v[32:47], v[224:227], v[244:247], v[32:47]
	s_mov_b64 s[0:1], 0xb00080
	s_add_u32 m0, s100, 0x8000
	v_lshl_add_u64 v[106:107], v[74:75], 0, s[0:1]
	global_load_lds_dwordx4 v[106:107], off
	ds_read_b128 v[236:239], v99 offset:20480
	s_waitcnt lgkmcnt(4)
	v_mfma_f32_32x32x16_bf16 v[16:31], v[228:231], v[240:243], v[16:31]
	v_mfma_f32_32x32x16_bf16 v[0:15], v[228:231], v[244:247], v[0:15]
	s_mov_b64 s[0:1], 0xb10080
	s_add_u32 m0, s100, 0x9000
	v_lshl_add_u64 v[106:107], v[74:75], 0, s[0:1]
	global_load_lds_dwordx4 v[106:107], off
	ds_read_b128 v[240:243], v104 offset:49152
	ds_read_b128 v[244:247], v104 offset:53248
	ds_read_b128 v[224:227], v100 offset:16384
	s_waitcnt lgkmcnt(4)
	v_mfma_f32_32x32x16_bf16 v[48:63], v[232:235], v[248:251], v[48:63]
	v_mfma_f32_32x32x16_bf16 v[32:47], v[232:235], v[252:255], v[32:47]
	s_mov_b64 s[0:1], 0xb20080
	s_add_u32 m0, s100, 0xa000
	v_lshl_add_u64 v[106:107], v[74:75], 0, s[0:1]
	global_load_lds_dwordx4 v[106:107], off
	ds_read_b128 v[228:231], v100 offset:20480
	s_waitcnt lgkmcnt(4)
	v_mfma_f32_32x32x16_bf16 v[16:31], v[236:239], v[248:251], v[16:31]
	v_mfma_f32_32x32x16_bf16 v[0:15], v[236:239], v[252:255], v[0:15]
	s_mov_b64 s[0:1], 0xb30080
	s_add_u32 m0, s100, 0xb000
	v_lshl_add_u64 v[106:107], v[74:75], 0, s[0:1]
	global_load_lds_dwordx4 v[106:107], off
	v_lshl_add_u64 v[74:75], v[74:75], 0, s[44:45]
	ds_read_b128 v[248:251], v105 offset:49152
	ds_read_b128 v[252:255], v105 offset:53248
	ds_read_b128 v[232:235], v101 offset:16384
	s_waitcnt lgkmcnt(4)
	v_mfma_f32_32x32x16_bf16 v[48:63], v[224:227], v[240:243], v[48:63]
	v_mfma_f32_32x32x16_bf16 v[32:47], v[224:227], v[244:247], v[32:47]
	ds_read_b128 v[236:239], v101 offset:20480
	s_waitcnt lgkmcnt(4)
	v_mfma_f32_32x32x16_bf16 v[16:31], v[228:231], v[240:243], v[16:31]
	v_mfma_f32_32x32x16_bf16 v[0:15], v[228:231], v[244:247], v[0:15]
	s_waitcnt lgkmcnt(0)
	s_waitcnt vmcnt(0)
	s_barrier
	s_add_u32 m0, s100, 0x4000
	v_lshl_add_u64 v[106:107], v[72:73], 0, s[96:97]
	global_load_lds_dwordx4 v[106:107], off
	s_add_u32 m0, s100, 0x5000
	v_lshl_add_u64 v[106:107], v[72:73], 0, s[50:51]
	global_load_lds_dwordx4 v[106:107], off
	s_add_u32 m0, s100, 0x6000
	v_lshl_add_u64 v[106:107], v[72:73], 0, s[24:25]
	global_load_lds_dwordx4 v[106:107], off
	s_add_u32 m0, s100, 0x7000
	v_lshl_add_u64 v[106:107], v[72:73], 0, s[26:27]
	global_load_lds_dwordx4 v[106:107], off
	v_lshl_add_u64 v[72:73], v[72:73], 0, s[44:45]
	ds_read_b128 v[240:243], v102 offset:32768
	ds_read_b128 v[244:247], v102 offset:36864
	ds_read_b128 v[224:227], v98
	v_mfma_f32_32x32x16_bf16 v[48:63], v[232:235], v[248:251], v[48:63]
	v_mfma_f32_32x32x16_bf16 v[32:47], v[232:235], v[252:255], v[32:47]
	ds_read_b128 v[228:231], v98 offset:4096
	v_mfma_f32_32x32x16_bf16 v[16:31], v[236:239], v[248:251], v[16:31]
	v_mfma_f32_32x32x16_bf16 v[0:15], v[236:239], v[252:255], v[0:15]
	s_add_u32 s101, s101, 2
	s_branch .Lgc_loop

; template <int EPI, int MI>
; DI void gemm_tile(const GemmDesc& g, int tm, int tn, char* smem) {
;     ...
;   const int rowA = wm * (32 * MI) + r, rowB = wn * 64 + r;
;   const int hk = hh ^ ((r & 7) ^ ((r >> 3) & 3));
;     ...
;   G_GLDS(0, 0);
;   asm volatile("s_waitcnt vmcnt(0)" ::: "memory");
;   __syncthreads();
;   for (int kt = 0; kt < nk; kt += 2) {
;     if (kt + 1 < nk) G_GLDS(kt + 1, 1);
;     G_COMPUTE(0);
;     asm volatile("s_waitcnt vmcnt(0)" ::: "memory");
;     __syncthreads();
;     if (kt + 1 < nk) {
;       if (kt + 2 < nk) G_GLDS(kt + 2, 0);
;       G_COMPUTE(1);
;       asm volatile("s_waitcnt vmcnt(0)" ::: "memory");
;       __syncthreads();
;     }
;   }
.Lgf_loop:
	ds_read_b128 v[248:251], v98 offset:32768
	ds_read_b128 v[252:255], v98 offset:36864
	ds_read_b128 v[232:235], v93
	s_waitcnt lgkmcnt(4)
	v_mfma_f32_32x32x16_bf16 v[48:63], v[224:227], v[240:243], v[48:63]
	v_mfma_f32_32x32x16_bf16 v[32:47], v[224:227], v[244:247], v[32:47]
	s_mov_b64 s[4:5], 0x1b80080
	s_add_u32 m0, s100, 0xc000
	v_lshl_add_u64 v[102:103], v[106:107], 0, s[4:5]
	global_load_lds_dwordx4 v[102:103], off
	ds_read_b128 v[236:239], v93 offset:4096
	s_waitcnt lgkmcnt(4)
	v_mfma_f32_32x32x16_bf16 v[16:31], v[228:231], v[240:243], v[16:31]
	v_mfma_f32_32x32x16_bf16 v[0:15], v[228:231], v[244:247], v[0:15]
	s_mov_b64 s[4:5], 0x1bac080
	s_add_u32 m0, s100, 0xd000
	v_lshl_add_u64 v[102:103], v[106:107], 0, s[4:5]
	global_load_lds_dwordx4 v[102:103], off
	ds_read_b128 v[240:243], v99 offset:32768
	ds_read_b128 v[244:247], v99 offset:36864
	ds_read_b128 v[224:227], v94
	s_waitcnt lgkmcnt(4)
	v_mfma_f32_32x32x16_bf16 v[48:63], v[232:235], v[248:251], v[48:63]
	v_mfma_f32_32x32x16_bf16 v[32:47], v[232:235], v[252:255], v[32:47]
	s_mov_b64 s[4:5], 0x1bd8080
	s_add_u32 m0, s100, 0xe000
	v_lshl_add_u64 v[102:103], v[106:107], 0, s[4:5]
	global_load_lds_dwordx4 v[102:103], off
	ds_read_b128 v[228:231], v94 offset:4096
	s_waitcnt lgkmcnt(4)
	v_mfma_f32_32x32x16_bf16 v[16:31], v[236:239], v[248:251], v[16:31]
	v_mfma_f32_32x32x16_bf16 v[0:15], v[236:239], v[252:255], v[0:15]
	s_mov_b64 s[4:5], 0x1c04080
	s_add_u32 m0, s100, 0xf000
	v_lshl_add_u64 v[102:103], v[106:107], 0, s[4:5]
	global_load_lds_dwordx4 v[102:103], off
	v_lshl_add_u64 v[106:107], v[106:107], 0, s[46:47]
	ds_read_b128 v[248:251], v100 offset:32768
	ds_read_b128 v[252:255], v100 offset:36864
	ds_read_b128 v[232:235], v95
	s_waitcnt lgkmcnt(4)
	v_mfma_f32_32x32x16_bf16 v[48:63], v[224:227], v[240:243], v[48:63]
	v_mfma_f32_32x32x16_bf16 v[32:47], v[224:227], v[244:247], v[32:47]
	ds_read_b128 v[236:239], v95 offset:4096
	s_waitcnt lgkmcnt(4)
	v_mfma_f32_32x32x16_bf16 v[16:31], v[228:231], v[240:243], v[16:31]
	v_mfma_f32_32x32x16_bf16 v[0:15], v[228:231], v[244:247], v[0:15]
	s_waitcnt lgkmcnt(0)
	s_waitcnt vmcnt(0)
	s_barrier
	s_cmp_eq_u32 s101, 42
	s_cbranch_scc1 .Lgf_noearly
	s_mov_b64 s[4:5], 0x5872080
	s_mov_b32 m0, s100
	v_lshl_add_u64 v[102:103], v[104:105], 0, s[4:5]
	global_load_lds_dwordx4 v[102:103], off
	s_mov_b64 s[4:5], 0x589e080
	s_add_u32 m0, s100, 0x1000
	v_lshl_add_u64 v[102:103], v[104:105], 0, s[4:5]
	global_load_lds_dwordx4 v[102:103], off
	s_mov_b64 s[4:5], 0x58ca080
	s_add_u32 m0, s100, 0x2000
	v_lshl_add_u64 v[102:103], v[104:105], 0, s[4:5]
	global_load_lds_dwordx4 v[102:103], off
	s_mov_b64 s[4:5], 0x58f6080
	s_add_u32 m0, s100, 0x3000
	v_lshl_add_u64 v[102:103], v[104:105], 0, s[4:5]
	global_load_lds_dwordx4 v[102:103], off
	v_lshl_add_u64 v[104:105], v[104:105], 0, s[46:47]
.Lgf_noearly:
	ds_read_b128 v[240:243], v97 offset:49152
	ds_read_b128 v[244:247], v97 offset:53248
	ds_read_b128 v[224:227], v92 offset:16384
	v_mfma_f32_32x32x16_bf16 v[48:63], v[232:235], v[248:251], v[48:63]
	v_mfma_f32_32x32x16_bf16 v[32:47], v[232:235], v[252:255], v[32:47]
	ds_read_b128 v[228:231], v92 offset:20480
	v_mfma_f32_32x32x16_bf16 v[16:31], v[236:239], v[248:251], v[16:31]
	v_mfma_f32_32x32x16_bf16 v[0:15], v[236:239], v[252:255], v[0:15]
	s_cmp_eq_u32 s101, 42
	s_cbranch_scc1 .Lgf_last
	ds_read_b128 v[248:251], v98 offset:49152
	ds_read_b128 v[252:255], v98 offset:53248
	ds_read_b128 v[232:235], v93 offset:16384
	s_waitcnt lgkmcnt(4)
	v_mfma_f32_32x32x16_bf16 v[48:63], v[224:227], v[240:243], v[48:63]
	v_mfma_f32_32x32x16_bf16 v[32:47], v[224:227], v[244:247], v[32:47]
	s_mov_b64 s[4:5], 0x1b80080
	s_add_u32 m0, s100, 0x8000
	v_lshl_add_u64 v[102:103], v[106:107], 0, s[4:5]
	global_load_lds_dwordx4 v[102:103], off
	ds_read_b128 v[236:239], v93 offset:20480
	s_waitcnt lgkmcnt(4)
	v_mfma_f32_32x32x16_bf16 v[16:31], v[228:231], v[240:243], v[16:31]
	v_mfma_f32_32x32x16_bf16 v[0:15], v[228:231], v[244:247], v[0:15]
	s_mov_b64 s[4:5], 0x1bac080
	s_add_u32 m0, s100, 0x9000
	v_lshl_add_u64 v[102:103], v[106:107], 0, s[4:5]
	global_load_lds_dwordx4 v[102:103], off
	ds_read_b128 v[240:243], v99 offset:49152
	ds_read_b128 v[244:247], v99 offset:53248
	ds_read_b128 v[224:227], v94 offset:16384
	s_waitcnt lgkmcnt(4)
	v_mfma_f32_32x32x16_bf16 v[48:63], v[232:235], v[248:251], v[48:63]
	v_mfma_f32_32x32x16_bf16 v[32:47], v[232:235], v[252:255], v[32:47]
	s_mov_b64 s[4:5], 0x1bd8080
	s_add_u32 m0, s100, 0xa000
	v_lshl_add_u64 v[102:103], v[106:107], 0, s[4:5]
	global_load_lds_dwordx4 v[102:103], off
	ds_read_b128 v[228:231], v94 offset:20480
	s_waitcnt lgkmcnt(4)
	v_mfma_f32_32x32x16_bf16 v[16:31], v[236:239], v[248:251], v[16:31]
	v_mfma_f32_32x32x16_bf16 v[0:15], v[236:239], v[252:255], v[0:15]
	s_mov_b64 s[4:5], 0x1c04080
	s_add_u32 m0, s100, 0xb000
	v_lshl_add_u64 v[102:103], v[106:107], 0, s[4:5]
	global_load_lds_dwordx4 v[102:103], off
	v_lshl_add_u64 v[106:107], v[106:107], 0, s[46:47]
	ds_read_b128 v[248:251], v100 offset:49152
	ds_read_b128 v[252:255], v100 offset:53248
	ds_read_b128 v[232:235], v95 offset:16384
	s_waitcnt lgkmcnt(4)
	v_mfma_f32_32x32x16_bf16 v[48:63], v[224:227], v[240:243], v[48:63]
	v_mfma_f32_32x32x16_bf16 v[32:47], v[224:227], v[244:247], v[32:47]
	ds_read_b128 v[236:239], v95 offset:20480
	s_waitcnt lgkmcnt(4)
	v_mfma_f32_32x32x16_bf16 v[16:31], v[228:231], v[240:243], v[16:31]
	v_mfma_f32_32x32x16_bf16 v[0:15], v[228:231], v[244:247], v[0:15]
	s_waitcnt lgkmcnt(0)
	s_waitcnt vmcnt(0)
	s_barrier
	s_mov_b64 s[4:5], 0x5872080
	s_add_u32 m0, s100, 0x4000
	v_lshl_add_u64 v[102:103], v[104:105], 0, s[4:5]
	global_load_lds_dwordx4 v[102:103], off
	s_mov_b64 s[4:5], 0x589e080
	s_add_u32 m0, s100, 0x5000
	v_lshl_add_u64 v[102:103], v[104:105], 0, s[4:5]
	global_load_lds_dwordx4 v[102:103], off
	s_mov_b64 s[4:5], 0x58ca080
	s_add_u32 m0, s100, 0x6000
	v_lshl_add_u64 v[102:103], v[104:105], 0, s[4:5]
	global_load_lds_dwordx4 v[102:103], off
	s_mov_b64 s[4:5], 0x58f6080
	s_add_u32 m0, s100, 0x7000
	v_lshl_add_u64 v[102:103], v[104:105], 0, s[4:5]
	global_load_lds_dwordx4 v[102:103], off
	v_lshl_add_u64 v[104:105], v[104:105], 0, s[46:47]
	ds_read_b128 v[240:243], v97 offset:32768
	ds_read_b128 v[244:247], v97 offset:36864
	ds_read_b128 v[224:227], v92
	v_mfma_f32_32x32x16_bf16 v[48:63], v[232:235], v[248:251], v[48:63]
	v_mfma_f32_32x32x16_bf16 v[32:47], v[232:235], v[252:255], v[32:47]
	ds_read_b128 v[228:231], v92 offset:4096
	v_mfma_f32_32x32x16_bf16 v[16:31], v[236:239], v[248:251], v[16:31]
	v_mfma_f32_32x32x16_bf16 v[0:15], v[236:239], v[252:255], v[0:15]
	s_add_u32 s101, s101, 2
	s_branch .Lgf_loop
